# forgetting attention: streamlined unmasked-tile body (in-place bias subtraction, V fragments hoisted, exp/cvt interleaved with PV MFMAs)
# speedup vs baseline: 1.0042x; 1.0042x over previous
; template <bool DIFF>
; __device__ __forceinline__ void attn_unit(CA& A, int l, int b, int hh, int qb, LAS unsigned char* lds, float lam, float lam_init) {
;     ...
;             const LAS unsigned char* Kb = lds + AL_KS + buf * AL_KSZ;
;             const LAS unsigned char* Vb = lds + AL_VT + buf * AL_VSZ;
;             f32x16 p[2];
; #pragma unroll
;             for (int kt = 0; kt < 2; ++kt) {
;                 if (!DIFF) {
;                     const LAS float* nc = (const LAS float*)(lds + AL_NC + buf * 512) + 32 * kt + 4 * hi;
; #pragma unroll
;                     for (int g = 0; g < 4; ++g) { const f32x4 c4 = *(const LAS f32x4*)(nc + 8 * g); p[kt][4 * g] = c4[0]; p[kt][4 * g + 1] = c4[1]; p[kt][4 * g + 2] = c4[2]; p[kt][4 * g + 3] = c4[3]; }
;                 }
; #pragma unroll
;                 for (int s = 0; s < NS; ++s) {
;                     const bf16x8 a = *(const LAS bf16x8*)(Kb + (32 * kt + r32) * 144 + (koff + 16 * s + 8 * hi) * 2);
;                     if (DIFF && s == 0) p[kt] = __builtin_amdgcn_mfma_f32_32x32x16_bf16(a, qf[s], negm, 0, 0, 0);
;                     else p[kt] = __builtin_amdgcn_mfma_f32_32x32x16_bf16(a, qf[s], p[kt], 0, 0, 0);
;                 }
;             }
;             if (!DIFF) {
; #pragma unroll
;                 for (int kt = 0; kt < 2; ++kt)
; #pragma unroll
;                     for (int r = 0; r < 16; ++r) p[kt][r] -= m_ref;
;             }
;             if (key0 + 63 > qfirst) {
; #pragma unroll
;                 for (int kt = 0; kt < 2; ++kt)
; #pragma unroll
;                     for (int r = 0; r < 16; ++r) if (key0 + 32 * kt + crow(r, hi) > qmine) p[kt][r] = -1e30f;
;             }
;             first = false;
; #pragma unroll
;             for (int kt = 0; kt < 2; ++kt)
; #pragma unroll
;                 for (int r = 0; r < 16; ++r) p[kt][r] = __builtin_amdgcn_exp2f(p[kt][r]);
;             bf16x8 pb[2][2];
; #pragma unroll
;             for (int kt = 0; kt < 2; ++kt)
; #pragma unroll
;                 for (int i = 0; i < 2; ++i) { v4u w;
; #pragma unroll
;                     for (int j = 0; j < 4; ++j) w[j] = pk2(p[kt][8 * i + 2 * j], p[kt][8 * i + 2 * j + 1]);
;                     pb[kt][i] = __builtin_bit_cast(bf16x8, w); }
; #pragma unroll
;             for (int kt = 0; kt < 2; ++kt)
; #pragma unroll
;                 for (int i = 0; i < 2; ++i) {
; #pragma unroll
.LBB0_786:
	s_mul_i32 s14, s17, 0x2400
	v_add3_u32 v15, v145, s14, v147
	v_lshl_add_u32 v14, s17, 9, v145
	ds_read_b128 v[2:5], v15
	ds_read_b128 v[80:83], v14 offset:35840
	ds_read_b128 v[84:87], v14 offset:35872
	ds_read_b128 v[88:91], v14 offset:35904
	ds_read_b128 v[92:95], v14 offset:35936
	ds_read_b128 v[6:9], v15 offset:32
	s_cmp_le_i32 s34, s26
	s_waitcnt lgkmcnt(1)
	v_mfma_f32_32x32x16_bf16 v[80:95], v[2:5], v[96:99], v[80:95]
	s_waitcnt lgkmcnt(0)
	v_mfma_f32_32x32x16_bf16 v[80:95], v[6:9], v[100:103], v[80:95]
	ds_read_b128 v[2:5], v15 offset:64
	ds_read_b128 v[6:9], v15 offset:4608
	ds_read_b128 v[10:13], v15 offset:96
	s_waitcnt lgkmcnt(2)
	v_mfma_f32_32x32x16_bf16 v[80:95], v[2:5], v[104:107], v[80:95]
	ds_read_b128 v[64:67], v14 offset:35968
	ds_read_b128 v[68:71], v14 offset:36000
	ds_read_b128 v[72:75], v14 offset:36032
	ds_read_b128 v[76:79], v14 offset:36064
	ds_read_b128 v[2:5], v15 offset:4640
	s_waitcnt lgkmcnt(1)
	v_mfma_f32_32x32x16_bf16 v[64:79], v[6:9], v[96:99], v[64:79]
	ds_read_b128 v[6:9], v15 offset:4672
	ds_read_b128 v[150:153], v15 offset:4704
	s_waitcnt lgkmcnt(2)
	v_mfma_f32_32x32x16_bf16 v[64:79], v[2:5], v[100:103], v[64:79]
	s_waitcnt lgkmcnt(1)
	v_mfma_f32_32x32x16_bf16 v[64:79], v[6:9], v[104:107], v[64:79]
	v_mfma_f32_32x32x16_bf16 v[80:95], v[10:13], v[108:111], v[80:95]
	s_waitcnt lgkmcnt(0)
	v_mfma_f32_32x32x16_bf16 v[64:79], v[150:153], v[108:111], v[64:79]
	s_cbranch_scc0 .Lmy_fox_masked
	s_mul_i32 s14, s17, 0x2200
	v_add3_u32 v14, v144, s14, v148
	v_mov_b32_e32 v204, s36
	v_mov_b32_e32 v205, s36
	v_add_u32_e32 v15, 0x5800, v14
	v_add_u32_e32 v14, 0x4800, v14
	v_mov_b32_e32 v206, s36
	v_mov_b32_e32 v207, s36
	ds_read2_b64 v[164:167], v14 offset0:0 offset1:2
	ds_read2_b64 v[168:171], v15 offset0:32 offset1:34
	ds_read2_b64 v[172:175], v14 offset0:4 offset1:6
	ds_read2_b64 v[180:183], v15 offset0:36 offset1:38
	ds_read2_b64 v[184:187], v14 offset0:8 offset1:10
	ds_read2_b64 v[188:191], v15 offset0:40 offset1:42
	ds_read2_b64 v[192:195], v14 offset0:12 offset1:14
	ds_read2_b64 v[196:199], v15 offset0:44 offset1:46
	v_pk_add_f32 v[80:81], v[80:81], v[126:127] neg_lo:[0,1] neg_hi:[0,1]
	v_pk_add_f32 v[82:83], v[82:83], v[126:127] neg_lo:[0,1] neg_hi:[0,1]
	v_pk_add_f32 v[84:85], v[84:85], v[126:127] neg_lo:[0,1] neg_hi:[0,1]
	v_pk_add_f32 v[86:87], v[86:87], v[126:127] neg_lo:[0,1] neg_hi:[0,1]
	v_pk_add_f32 v[88:89], v[88:89], v[126:127] neg_lo:[0,1] neg_hi:[0,1]
	v_pk_add_f32 v[90:91], v[90:91], v[126:127] neg_lo:[0,1] neg_hi:[0,1]
	v_pk_add_f32 v[92:93], v[92:93], v[126:127] neg_lo:[0,1] neg_hi:[0,1]
	v_pk_add_f32 v[94:95], v[94:95], v[126:127] neg_lo:[0,1] neg_hi:[0,1]
	v_pk_add_f32 v[64:65], v[64:65], v[126:127] neg_lo:[0,1] neg_hi:[0,1]
	v_pk_add_f32 v[66:67], v[66:67], v[126:127] neg_lo:[0,1] neg_hi:[0,1]
	v_pk_add_f32 v[68:69], v[68:69], v[126:127] neg_lo:[0,1] neg_hi:[0,1]
	v_pk_add_f32 v[70:71], v[70:71], v[126:127] neg_lo:[0,1] neg_hi:[0,1]
	v_pk_add_f32 v[72:73], v[72:73], v[126:127] neg_lo:[0,1] neg_hi:[0,1]
	v_pk_add_f32 v[74:75], v[74:75], v[126:127] neg_lo:[0,1] neg_hi:[0,1]
	v_pk_add_f32 v[76:77], v[76:77], v[126:127] neg_lo:[0,1] neg_hi:[0,1]
	v_pk_add_f32 v[78:79], v[78:79], v[126:127] neg_lo:[0,1] neg_hi:[0,1]
	v_exp_f32_e32 v80, v80
	v_exp_f32_e32 v81, v81
	v_exp_f32_e32 v82, v82
	v_exp_f32_e32 v83, v83
	v_exp_f32_e32 v84, v84
	v_exp_f32_e32 v85, v85
	v_exp_f32_e32 v86, v86
	v_exp_f32_e32 v87, v87
	v_cvt_pk_bf16_f32 v80, v80, v81
	v_cvt_pk_bf16_f32 v81, v82, v83
	v_cvt_pk_bf16_f32 v82, v84, v85
	v_cvt_pk_bf16_f32 v83, v86, v87
	v_exp_f32_e32 v88, v88
	v_exp_f32_e32 v89, v89
	s_waitcnt lgkmcnt(6)
	v_mfma_f32_32x32x16_bf16 v[32:47], v[164:167], v[80:83], v[32:47]
	v_exp_f32_e32 v90, v90
	v_exp_f32_e32 v91, v91
	v_cvt_pk_bf16_f32 v84, v88, v89
	v_mfma_f32_32x32x16_bf16 v[16:31], v[168:171], v[80:83], v[16:31]
	v_exp_f32_e32 v92, v92
	v_exp_f32_e32 v93, v93
	v_cvt_pk_bf16_f32 v85, v90, v91
	v_mfma_f32_32x32x16_bf16 v[48:63], v[204:207], v[80:83], v[48:63]
	v_exp_f32_e32 v94, v94
	v_exp_f32_e32 v95, v95
	v_cvt_pk_bf16_f32 v86, v92, v93
	v_exp_f32_e32 v64, v64
	v_cvt_pk_bf16_f32 v87, v94, v95
	v_exp_f32_e32 v65, v65
	s_waitcnt lgkmcnt(4)
	v_mfma_f32_32x32x16_bf16 v[32:47], v[172:175], v[84:87], v[32:47]
	v_exp_f32_e32 v66, v66
	v_exp_f32_e32 v67, v67
	v_cvt_pk_bf16_f32 v64, v64, v65
	v_mfma_f32_32x32x16_bf16 v[16:31], v[180:183], v[84:87], v[16:31]
	v_exp_f32_e32 v68, v68
	v_exp_f32_e32 v69, v69
	v_cvt_pk_bf16_f32 v65, v66, v67
	v_mfma_f32_32x32x16_bf16 v[48:63], v[204:207], v[84:87], v[48:63]
	v_exp_f32_e32 v70, v70
	v_exp_f32_e32 v71, v71
	v_cvt_pk_bf16_f32 v66, v68, v69
	v_exp_f32_e32 v72, v72
	v_cvt_pk_bf16_f32 v67, v70, v71
	v_exp_f32_e32 v73, v73
	s_waitcnt lgkmcnt(2)
	v_mfma_f32_32x32x16_bf16 v[32:47], v[184:187], v[64:67], v[32:47]
	v_exp_f32_e32 v74, v74
	v_exp_f32_e32 v75, v75
	v_cvt_pk_bf16_f32 v68, v72, v73
	v_mfma_f32_32x32x16_bf16 v[16:31], v[188:191], v[64:67], v[16:31]
	v_exp_f32_e32 v76, v76
	v_exp_f32_e32 v77, v77
	v_cvt_pk_bf16_f32 v69, v74, v75
	v_mfma_f32_32x32x16_bf16 v[48:63], v[204:207], v[64:67], v[48:63]
	v_exp_f32_e32 v78, v78
	v_exp_f32_e32 v79, v79
	v_cvt_pk_bf16_f32 v70, v76, v77
	s_nop 0
	v_cvt_pk_bf16_f32 v71, v78, v79
	s_waitcnt lgkmcnt(0)
	s_nop 0
	v_mfma_f32_32x32x16_bf16 v[32:47], v[192:195], v[68:71], v[32:47]
	v_mfma_f32_32x32x16_bf16 v[16:31], v[196:199], v[68:71], v[16:31]
	v_mfma_f32_32x32x16_bf16 v[48:63], v[204:207], v[68:71], v[48:63]
	s_mov_b64 s[14:15], 0
	s_branch .Lmy_fox_join
; __device__ __forceinline__ int crow(int r, int hi) { return (r & 3) + 8 * (r >> 2) + 4 * hi; }
; template <bool DIFF>
; __device__ __forceinline__ void attn_unit(CA& A, int l, int b, int hh, int qb, LAS unsigned char* lds, float lam, float lam_init) {
;     ...
;             if (!DIFF) {
; #pragma unroll
;                 for (int kt = 0; kt < 2; ++kt)
; #pragma unroll
;                     for (int r = 0; r < 16; ++r) p[kt][r] -= m_ref;
;             }
;             if (key0 + 63 > qfirst) {
; #pragma unroll
;                 for (int kt = 0; kt < 2; ++kt)
; #pragma unroll
;                     for (int r = 0; r < 16; ++r) if (key0 + 32 * kt + crow(r, hi) > qmine) p[kt][r] = -1e30f;
;             }
.Lmy_fox_masked:
	s_nop 9
	v_mov_b32_e32 v2, v87
	v_mov_b32_e32 v3, v88
	v_mov_b32_e32 v11, v82
	v_mov_b32_e32 v12, v83
	v_mov_b32_e32 v14, v85
	v_mov_b32_e32 v15, v86
	v_pk_add_f32 v[82:83], v[2:3], v[126:127] neg_lo:[0,1] neg_hi:[0,1]
	v_mov_b32_e32 v2, v89
	v_mov_b32_e32 v3, v90
	v_pk_add_f32 v[132:133], v[14:15], v[126:127] neg_lo:[0,1] neg_hi:[0,1]
	v_pk_add_f32 v[14:15], v[2:3], v[126:127] neg_lo:[0,1] neg_hi:[0,1]
	v_mov_b32_e32 v2, v91
	v_mov_b32_e32 v3, v92
	v_sub_f32_e32 v149, v80, v126
	v_mov_b32_e32 v10, v81
	v_pk_add_f32 v[80:81], v[2:3], v[126:127] neg_lo:[0,1] neg_hi:[0,1]
	v_mov_b32_e32 v2, v93
	v_mov_b32_e32 v3, v94
	v_mov_b32_e32 v13, v84
	v_pk_add_f32 v[84:85], v[2:3], v[126:127] neg_lo:[0,1] neg_hi:[0,1]
	v_pk_mov_b32 v[2:3], v[94:95], v[64:65] op_sel:[1,0]
	v_pk_add_f32 v[134:135], v[10:11], v[126:127] neg_lo:[0,1] neg_hi:[0,1]
	v_pk_add_f32 v[10:11], v[2:3], v[126:127] neg_lo:[0,1] neg_hi:[0,1]
	v_mov_b32_e32 v2, v65
	v_mov_b32_e32 v3, v66
	v_pk_add_f32 v[130:131], v[12:13], v[126:127] neg_lo:[0,1] neg_hi:[0,1]
	v_pk_add_f32 v[12:13], v[2:3], v[126:127] neg_lo:[0,1] neg_hi:[0,1]
	v_mov_b32_e32 v2, v67
	v_mov_b32_e32 v3, v68
	v_pk_add_f32 v[66:67], v[2:3], v[126:127] neg_lo:[0,1] neg_hi:[0,1]
	v_mov_b32_e32 v2, v69
	v_mov_b32_e32 v3, v70
	v_mov_b32_e32 v6, v75
	v_mov_b32_e32 v7, v76
	v_pk_add_f32 v[64:65], v[2:3], v[126:127] neg_lo:[0,1] neg_hi:[0,1]
	v_mov_b32_e32 v2, v71
	v_mov_b32_e32 v3, v72
	v_mov_b32_e32 v4, v73
	v_mov_b32_e32 v5, v74
	v_pk_add_f32 v[8:9], v[6:7], v[126:127] neg_lo:[0,1] neg_hi:[0,1]
	v_mov_b32_e32 v6, v77
	v_mov_b32_e32 v7, v78
	v_pk_add_f32 v[2:3], v[2:3], v[126:127] neg_lo:[0,1] neg_hi:[0,1]
	v_pk_add_f32 v[4:5], v[4:5], v[126:127] neg_lo:[0,1] neg_hi:[0,1]
	v_pk_add_f32 v[6:7], v[6:7], v[126:127] neg_lo:[0,1] neg_hi:[0,1]
	v_sub_f32_e32 v68, v79, v126
	s_cbranch_scc1 .LBB0_788
	v_add_u32_e32 v69, s34, v142
	v_subrev_u32_e32 v70, 63, v69
	v_cmp_gt_i32_e32 vcc, v70, v120
	s_nop 1
	v_cndmask_b32_e32 v71, v149, v225, vcc
	v_cmp_lt_i32_e32 vcc, v70, v120
	v_subrev_u32_e32 v70, 61, v69
	s_nop 0
	v_cndmask_b32_e32 v149, v71, v149, vcc
	v_cndmask_b32_e32 v134, v225, v134, vcc
	v_cmp_le_i32_e32 vcc, v70, v120
	v_subrev_u32_e32 v70, 60, v69
	s_nop 0
	v_cndmask_b32_e32 v135, v225, v135, vcc
	v_cmp_le_i32_e32 vcc, v70, v120
	v_subrev_u32_e32 v70, 55, v69
	s_nop 0
	v_cndmask_b32_e32 v130, v225, v130, vcc
	v_cmp_le_i32_e32 vcc, v70, v120
	v_subrev_u32_e32 v70, 54, v69
	s_nop 0
	v_cndmask_b32_e32 v131, v225, v131, vcc
	v_cmp_le_i32_e32 vcc, v70, v120
	v_subrev_u32_e32 v70, 53, v69
	s_nop 0
	v_cndmask_b32_e32 v132, v225, v132, vcc
	v_cmp_le_i32_e32 vcc, v70, v120
	v_subrev_u32_e32 v70, 52, v69
	s_nop 0
	v_cndmask_b32_e32 v133, v225, v133, vcc
	v_cmp_le_i32_e32 vcc, v70, v120
	v_subrev_u32_e32 v70, 47, v69
	s_nop 0
	v_cndmask_b32_e32 v82, v225, v82, vcc
	v_cmp_le_i32_e32 vcc, v70, v120
	v_subrev_u32_e32 v70, 46, v69
	s_nop 0
	v_cndmask_b32_e32 v83, v225, v83, vcc
	v_cmp_le_i32_e32 vcc, v70, v120
	v_subrev_u32_e32 v70, 45, v69
	s_nop 0
	v_cndmask_b32_e32 v14, v225, v14, vcc
	v_cmp_le_i32_e32 vcc, v70, v120
	v_subrev_u32_e32 v70, 44, v69
	s_nop 0
	v_cndmask_b32_e32 v15, v225, v15, vcc
	v_cmp_le_i32_e32 vcc, v70, v120
	v_subrev_u32_e32 v70, 39, v69
	s_nop 0
	v_cndmask_b32_e32 v80, v225, v80, vcc
	v_cmp_le_i32_e32 vcc, v70, v120
	v_subrev_u32_e32 v70, 38, v69
	s_nop 0
	v_cndmask_b32_e32 v81, v225, v81, vcc
	v_cmp_le_i32_e32 vcc, v70, v120
	v_subrev_u32_e32 v70, 37, v69
	s_nop 0
	v_cndmask_b32_e32 v84, v225, v84, vcc
	v_cmp_le_i32_e32 vcc, v70, v120
	v_subrev_u32_e32 v70, 36, v69
	s_nop 0
	v_cndmask_b32_e32 v85, v225, v85, vcc
	v_cmp_le_i32_e32 vcc, v70, v120
	v_subrev_u32_e32 v70, 31, v69
	s_nop 0
	v_cndmask_b32_e32 v10, v225, v10, vcc
	v_cmp_le_i32_e32 vcc, v70, v120
	v_subrev_u32_e32 v70, 30, v69
	s_nop 0
	v_cndmask_b32_e32 v11, v225, v11, vcc
	v_cmp_le_i32_e32 vcc, v70, v120
	v_subrev_u32_e32 v70, 29, v69
	s_nop 0
	v_cndmask_b32_e32 v12, v225, v12, vcc
	v_cmp_le_i32_e32 vcc, v70, v120
	v_subrev_u32_e32 v70, 28, v69
	s_nop 0
	v_cndmask_b32_e32 v13, v225, v13, vcc
	v_cmp_le_i32_e32 vcc, v70, v120
	v_subrev_u32_e32 v70, 23, v69
	s_nop 0
	v_cndmask_b32_e32 v66, v225, v66, vcc
	v_cmp_le_i32_e32 vcc, v70, v120
	v_subrev_u32_e32 v70, 22, v69
	s_nop 0
	v_cndmask_b32_e32 v67, v225, v67, vcc
	v_cmp_le_i32_e32 vcc, v70, v120
	v_subrev_u32_e32 v70, 21, v69
	s_nop 0
	v_cndmask_b32_e32 v64, v225, v64, vcc
	v_cmp_le_i32_e32 vcc, v70, v120
	v_subrev_u32_e32 v70, 20, v69
	s_nop 0
	v_cndmask_b32_e32 v65, v225, v65, vcc
	v_cmp_le_i32_e32 vcc, v70, v120
	v_add_u32_e32 v70, -15, v69
	s_nop 0
	v_cndmask_b32_e32 v2, v225, v2, vcc
	v_cmp_le_i32_e32 vcc, v70, v120
	v_add_u32_e32 v70, -14, v69
	s_nop 0
	v_cndmask_b32_e32 v3, v225, v3, vcc
	v_cmp_le_i32_e32 vcc, v70, v120
	v_add_u32_e32 v70, -13, v69
	s_nop 0
	v_cndmask_b32_e32 v4, v225, v4, vcc
	v_cmp_le_i32_e32 vcc, v70, v120
	v_add_u32_e32 v70, -12, v69
	s_nop 0
	v_cndmask_b32_e32 v5, v225, v5, vcc
	v_cmp_le_i32_e32 vcc, v70, v120
	v_add_u32_e32 v70, -7, v69
	s_nop 0
	v_cndmask_b32_e32 v8, v225, v8, vcc
	v_cmp_le_i32_e32 vcc, v70, v120
	v_add_u32_e32 v70, -6, v69
	s_nop 0
	v_cndmask_b32_e32 v9, v225, v9, vcc
	v_cmp_le_i32_e32 vcc, v70, v120
	v_add_u32_e32 v70, -5, v69
	v_add_u32_e32 v69, -4, v69
	v_cndmask_b32_e32 v6, v225, v6, vcc
	v_cmp_le_i32_e32 vcc, v70, v120
	s_nop 1
	v_cndmask_b32_e32 v7, v225, v7, vcc
	v_cmp_le_i32_e32 vcc, v69, v120
	s_nop 1
	v_cndmask_b32_e32 v68, v225, v68, vcc

; template <bool DIFF>
; __device__ __forceinline__ void attn_unit(CA& A, int l, int b, int hh, int qb, LAS unsigned char* lds, float lam, float lam_init) {
;     ...
;         }
;         if (has_next) ATT_WRITE(buf ^ 1);
;         if (!DIFF) {
;             const int vote = (!first && !__any(nc_hi + qkb - m_ref + 2.0f * qkb >= -48.0f)) ? 1 : 0;
;             if (lane == 0) votes[(tt & 1) * 8 + wid] = vote;
;         }
;         __syncthreads();
;         if (!has_next) break;
;         if (!DIFF) {
;             const int pb_ = (tt & 1) * 8;
;             const int all = votes[pb_] & votes[pb_ + 1] & votes[pb_ + 2] & votes[pb_ + 3] & votes[pb_ + 4] & votes[pb_ + 5] & votes[pb_ + 6] & votes[pb_ + 7];
;             if (all) break;
;         }
.Lmy_fox_join:
	s_andn2_b64 vcc, exec, s[12:13]
	s_cbranch_vccz .LBB0_778
